# FFN1: first two vmcnt waits of each non-first unit relaxed to vmcnt(16) so the epilogue's 8 stores need not be acknowledged before the next unit's first segments (in-order completion keeps the require
# speedup vs baseline: 1.0077x; 1.0077x over previous
.LBB0_1137:
	s_ashr_i32 s37, s36, 31
	s_lshl_b64 s[18:19], s[36:37], 19
	s_add_u32 s40, s96, s18
	s_addc_u32 s41, s97, s19
	s_and_b64 s[18:19], s[42:43], exec
	s_cselect_b32 s17, s41, s59
	s_cselect_b32 s37, s40, s58
	s_ashr_i32 s39, s38, 31
	s_lshl_b64 s[18:19], s[38:39], 19
	s_add_u32 s48, s5, s18
	s_addc_u32 s49, s6, s19
	s_and_b64 s[18:19], s[42:43], exec
	s_cselect_b32 s39, s49, s51
	s_cselect_b32 s46, s48, s50
	s_add_u32 s58, s58, 0x40080
	s_addc_u32 s59, s59, 0
	s_add_u32 s47, s50, 0x100
	s_addc_u32 s62, s51, 0
	s_mov_b32 s63, -2
	s_add_u32 s18, s58, 0xfffc0080
	s_addc_u32 s19, s59, -1
	s_add_i32 s20, 0, 0x10000
	s_cmp_eq_u32 s63, 12
	s_cselect_b32 s61, s17, s19
	s_cselect_b32 s60, s37, s18
	v_add_u32_e32 v140, s20, v143
	s_cselect_b32 s51, s39, s62
	s_cselect_b32 s50, s46, s47
	s_add_i32 s21, 0, 0x14000
	ds_read_b128 v[146:149], v140
	ds_read_b128 v[150:153], v140 offset:1024
	ds_read_b128 v[154:157], v140 offset:2048
	ds_read_b128 v[164:167], v140 offset:3072
	v_add_u32_e32 v140, s21, v143
	ds_read_b128 v[168:171], v140
	ds_read_b128 v[172:175], v140 offset:1024
	ds_read_b128 v[176:179], v140 offset:2048
	ds_read_b128 v[180:183], v140 offset:3072
	v_lshl_add_u64 v[140:141], s[58:59], 0, v[136:137]
	s_add_i32 m0, s8, 0xc000
	ds_read_b128 v[184:187], v144
	ds_read_b128 v[188:191], v144 offset:1024
	ds_read_b128 v[192:195], v144 offset:2048
	ds_read_b128 v[196:199], v144 offset:3072
	ds_read_b128 v[206:209], v144 offset:4096
	ds_read_b128 v[210:213], v144 offset:5120
	ds_read_b128 v[214:217], v144 offset:6144
	ds_read_b128 v[218:221], v144 offset:7168
	global_load_lds_dwordx4 v[140:141], off
	v_lshl_add_u64 v[140:141], s[58:59], 0, v[138:139]
	s_add_i32 m0, s8, 0xe000
	s_nop 0
	global_load_lds_dwordx4 v[140:141], off
	s_cmp_lt_u32 s14, 2
	s_cbranch_scc1 .Lw1138a_std
	s_waitcnt vmcnt(16)
	s_branch .Lw1138a_done

.Lw1138a_done:
	s_waitcnt lgkmcnt(0)
	s_setprio 1
	s_barrier
	v_mfma_f32_16x16x32_bf16 v[124:127], v[146:149], v[184:187], 0
	v_mfma_f32_16x16x32_bf16 v[120:123], v[154:157], v[184:187], 0
	v_mfma_f32_16x16x32_bf16 v[108:111], v[146:149], v[192:195], 0
	v_mfma_f32_16x16x32_bf16 v[104:107], v[154:157], v[192:195], 0
	v_mfma_f32_16x16x32_bf16 v[92:95], v[146:149], v[206:209], 0
	v_mfma_f32_16x16x32_bf16 v[88:91], v[154:157], v[206:209], 0
	v_mfma_f32_16x16x32_bf16 v[76:79], v[146:149], v[214:217], 0
	v_mfma_f32_16x16x32_bf16 v[72:75], v[154:157], v[214:217], 0
	v_mfma_f32_16x16x32_bf16 v[124:127], v[150:153], v[188:191], v[124:127]
	v_mfma_f32_16x16x32_bf16 v[120:123], v[164:167], v[188:191], v[120:123]
	v_mfma_f32_16x16x32_bf16 v[108:111], v[150:153], v[196:199], v[108:111]
	v_mfma_f32_16x16x32_bf16 v[104:107], v[164:167], v[196:199], v[104:107]
	v_mfma_f32_16x16x32_bf16 v[92:95], v[150:153], v[210:213], v[92:95]
	v_mfma_f32_16x16x32_bf16 v[88:91], v[164:167], v[210:213], v[88:91]
	v_mfma_f32_16x16x32_bf16 v[76:79], v[150:153], v[218:221], v[76:79]
	v_mfma_f32_16x16x32_bf16 v[72:75], v[164:167], v[218:221], v[72:75]
	s_setprio 0
	s_setprio 1
	v_mfma_f32_16x16x32_bf16 v[116:119], v[168:171], v[184:187], 0
	v_mfma_f32_16x16x32_bf16 v[112:115], v[176:179], v[184:187], 0
	v_mfma_f32_16x16x32_bf16 v[100:103], v[168:171], v[192:195], 0
	v_mfma_f32_16x16x32_bf16 v[96:99], v[176:179], v[192:195], 0
	v_mfma_f32_16x16x32_bf16 v[84:87], v[168:171], v[206:209], 0
	v_mfma_f32_16x16x32_bf16 v[80:83], v[176:179], v[206:209], 0
	v_mfma_f32_16x16x32_bf16 v[68:71], v[168:171], v[214:217], 0
	v_mfma_f32_16x16x32_bf16 v[64:67], v[176:179], v[214:217], 0
	v_mfma_f32_16x16x32_bf16 v[116:119], v[172:175], v[188:191], v[116:119]
	v_mfma_f32_16x16x32_bf16 v[112:115], v[180:183], v[188:191], v[112:115]
	v_mfma_f32_16x16x32_bf16 v[100:103], v[172:175], v[196:199], v[100:103]
	v_mfma_f32_16x16x32_bf16 v[96:99], v[180:183], v[196:199], v[96:99]
	v_mfma_f32_16x16x32_bf16 v[84:87], v[172:175], v[210:213], v[84:87]
	v_mfma_f32_16x16x32_bf16 v[80:83], v[180:183], v[210:213], v[80:83]
	v_mfma_f32_16x16x32_bf16 v[68:71], v[172:175], v[218:221], v[68:71]
	v_mfma_f32_16x16x32_bf16 v[64:67], v[180:183], v[218:221], v[64:67]
	s_barrier
	s_setprio 0
	s_add_i32 s18, s20, s7
	v_lshl_add_u64 v[140:141], s[50:51], 0, v[132:133]
	s_mov_b32 m0, s18
	ds_read_b128 v[184:187], v144 offset:16384
	ds_read_b128 v[188:191], v144 offset:17408
	ds_read_b128 v[192:195], v144 offset:18432
	ds_read_b128 v[196:199], v144 offset:19456
	ds_read_b128 v[206:209], v144 offset:20480
	ds_read_b128 v[210:213], v144 offset:21504
	ds_read_b128 v[214:217], v144 offset:22528
	ds_read_b128 v[218:221], v144 offset:23552
	global_load_lds_dwordx4 v[140:141], off
	s_add_i32 m0, s18, 0x2000
	s_add_u32 s18, s50, 0x40000
	v_lshl_add_u64 v[158:159], s[50:51], 0, v[128:129]
	s_addc_u32 s19, s51, 0
	s_add_i32 s20, s21, s7
	global_load_lds_dwordx4 v[158:159], off
	v_lshl_add_u64 v[200:201], s[18:19], 0, v[132:133]
	s_mov_b32 m0, s20
	v_lshl_add_u64 v[222:223], s[60:61], 0, v[130:131]
	global_load_lds_dwordx4 v[200:201], off
	v_lshl_add_u64 v[200:201], s[18:19], 0, v[128:129]
	s_add_i32 m0, s20, 0x2000
	s_nop 0
	global_load_lds_dwordx4 v[200:201], off
	v_lshl_add_u64 v[200:201], s[60:61], 0, v[134:135]
	s_mov_b32 m0, s8
	s_nop 0
	global_load_lds_dwordx4 v[200:201], off
	s_mov_b32 m0, s9
	s_nop 0
	global_load_lds_dwordx4 v[222:223], off
	s_cmp_lt_u32 s14, 2
	s_cbranch_scc1 .Lw1138b_std
	s_waitcnt vmcnt(16)
	s_branch .Lw1138b_done

.Lw1138b_done:
	s_waitcnt lgkmcnt(0)
	s_setprio 1
	s_barrier
	v_mfma_f32_16x16x32_bf16 v[60:63], v[146:149], v[184:187], 0
	v_mfma_f32_16x16x32_bf16 v[56:59], v[154:157], v[184:187], 0
	v_mfma_f32_16x16x32_bf16 v[44:47], v[146:149], v[192:195], 0
	v_mfma_f32_16x16x32_bf16 v[40:43], v[154:157], v[192:195], 0
	v_mfma_f32_16x16x32_bf16 v[28:31], v[146:149], v[206:209], 0
	v_mfma_f32_16x16x32_bf16 v[24:27], v[154:157], v[206:209], 0
	v_mfma_f32_16x16x32_bf16 v[12:15], v[146:149], v[214:217], 0
	v_mfma_f32_16x16x32_bf16 v[8:11], v[154:157], v[214:217], 0
	v_mfma_f32_16x16x32_bf16 v[60:63], v[150:153], v[188:191], v[60:63]
	v_mfma_f32_16x16x32_bf16 v[56:59], v[164:167], v[188:191], v[56:59]
	v_mfma_f32_16x16x32_bf16 v[44:47], v[150:153], v[196:199], v[44:47]
	v_mfma_f32_16x16x32_bf16 v[40:43], v[164:167], v[196:199], v[40:43]
	v_mfma_f32_16x16x32_bf16 v[28:31], v[150:153], v[210:213], v[28:31]
	v_mfma_f32_16x16x32_bf16 v[24:27], v[164:167], v[210:213], v[24:27]
	v_mfma_f32_16x16x32_bf16 v[12:15], v[150:153], v[218:221], v[12:15]
	v_mfma_f32_16x16x32_bf16 v[8:11], v[164:167], v[218:221], v[8:11]
	s_setprio 0
	s_setprio 1
	v_mfma_f32_16x16x32_bf16 v[52:55], v[168:171], v[184:187], 0
	v_mfma_f32_16x16x32_bf16 v[48:51], v[176:179], v[184:187], 0
	v_mfma_f32_16x16x32_bf16 v[36:39], v[168:171], v[192:195], 0
	v_mfma_f32_16x16x32_bf16 v[32:35], v[176:179], v[192:195], 0
	v_mfma_f32_16x16x32_bf16 v[20:23], v[168:171], v[206:209], 0
	v_mfma_f32_16x16x32_bf16 v[16:19], v[176:179], v[206:209], 0
	v_mfma_f32_16x16x32_bf16 v[4:7], v[168:171], v[214:217], 0
	v_mfma_f32_16x16x32_bf16 v[0:3], v[176:179], v[214:217], 0
	v_mfma_f32_16x16x32_bf16 v[52:55], v[172:175], v[188:191], v[52:55]
	v_mfma_f32_16x16x32_bf16 v[48:51], v[180:183], v[188:191], v[48:51]
	v_mfma_f32_16x16x32_bf16 v[36:39], v[172:175], v[196:199], v[36:39]
	v_mfma_f32_16x16x32_bf16 v[32:35], v[180:183], v[196:199], v[32:35]
	v_mfma_f32_16x16x32_bf16 v[20:23], v[172:175], v[210:213], v[20:23]
	v_mfma_f32_16x16x32_bf16 v[16:19], v[180:183], v[210:213], v[16:19]
	v_mfma_f32_16x16x32_bf16 v[4:7], v[172:175], v[218:221], v[4:7]
	v_mfma_f32_16x16x32_bf16 v[0:3], v[180:183], v[218:221], v[0:3]
	s_barrier
	s_setprio 0
	s_add_i32 s20, 0, 0x18000
	v_add_u32_e32 v145, s20, v143
	s_add_i32 s21, 0, 0x1c000
	ds_read_b128 v[146:149], v145
	ds_read_b128 v[150:153], v145 offset:1024
	ds_read_b128 v[154:157], v145 offset:2048
	ds_read_b128 v[164:167], v145 offset:3072
	v_add_u32_e32 v145, s21, v143
	ds_read_b128 v[168:171], v145
	ds_read_b128 v[172:175], v145 offset:1024
	ds_read_b128 v[176:179], v145 offset:2048
	ds_read_b128 v[180:183], v145 offset:3072
	s_add_u32 s18, s60, 0x40000
	s_addc_u32 s19, s61, 0
	s_mov_b32 m0, s10
	v_lshl_add_u64 v[224:225], s[18:19], 0, v[134:135]
	ds_read_b128 v[184:187], v144 offset:32768
	ds_read_b128 v[188:191], v144 offset:33792
	ds_read_b128 v[192:195], v144 offset:34816
	ds_read_b128 v[196:199], v144 offset:35840
	ds_read_b128 v[206:209], v144 offset:36864
	ds_read_b128 v[210:213], v144 offset:37888
	ds_read_b128 v[214:217], v144 offset:38912
	ds_read_b128 v[218:221], v144 offset:39936
	global_load_lds_dwordx4 v[224:225], off
	v_lshl_add_u64 v[224:225], s[18:19], 0, v[130:131]
	s_mov_b32 m0, s11
	s_nop 0
	global_load_lds_dwordx4 v[224:225], off
	s_waitcnt vmcnt(8)
	s_waitcnt lgkmcnt(0)
	s_setprio 1
	s_barrier
	v_mfma_f32_16x16x32_bf16 v[124:127], v[146:149], v[184:187], v[124:127]
	v_mfma_f32_16x16x32_bf16 v[120:123], v[154:157], v[184:187], v[120:123]
	v_mfma_f32_16x16x32_bf16 v[108:111], v[146:149], v[192:195], v[108:111]
	v_mfma_f32_16x16x32_bf16 v[104:107], v[154:157], v[192:195], v[104:107]
	v_mfma_f32_16x16x32_bf16 v[92:95], v[146:149], v[206:209], v[92:95]
	v_mfma_f32_16x16x32_bf16 v[88:91], v[154:157], v[206:209], v[88:91]
	v_mfma_f32_16x16x32_bf16 v[76:79], v[146:149], v[214:217], v[76:79]
	v_mfma_f32_16x16x32_bf16 v[72:75], v[154:157], v[214:217], v[72:75]
	v_mfma_f32_16x16x32_bf16 v[124:127], v[150:153], v[188:191], v[124:127]
	v_mfma_f32_16x16x32_bf16 v[120:123], v[164:167], v[188:191], v[120:123]
	v_mfma_f32_16x16x32_bf16 v[108:111], v[150:153], v[196:199], v[108:111]
	v_mfma_f32_16x16x32_bf16 v[104:107], v[164:167], v[196:199], v[104:107]
	v_mfma_f32_16x16x32_bf16 v[92:95], v[150:153], v[210:213], v[92:95]
	v_mfma_f32_16x16x32_bf16 v[88:91], v[164:167], v[210:213], v[88:91]
	v_mfma_f32_16x16x32_bf16 v[76:79], v[150:153], v[218:221], v[76:79]
	v_mfma_f32_16x16x32_bf16 v[72:75], v[164:167], v[218:221], v[72:75]
	s_setprio 0
	s_setprio 1
	v_mfma_f32_16x16x32_bf16 v[116:119], v[168:171], v[184:187], v[116:119]
	v_mfma_f32_16x16x32_bf16 v[112:115], v[176:179], v[184:187], v[112:115]
	v_mfma_f32_16x16x32_bf16 v[100:103], v[168:171], v[192:195], v[100:103]
	v_mfma_f32_16x16x32_bf16 v[96:99], v[176:179], v[192:195], v[96:99]
	v_mfma_f32_16x16x32_bf16 v[84:87], v[168:171], v[206:209], v[84:87]
	v_mfma_f32_16x16x32_bf16 v[80:83], v[176:179], v[206:209], v[80:83]
	v_mfma_f32_16x16x32_bf16 v[68:71], v[168:171], v[214:217], v[68:71]
	v_mfma_f32_16x16x32_bf16 v[64:67], v[176:179], v[214:217], v[64:67]
	v_mfma_f32_16x16x32_bf16 v[116:119], v[172:175], v[188:191], v[116:119]
	v_mfma_f32_16x16x32_bf16 v[112:115], v[180:183], v[188:191], v[112:115]
	v_mfma_f32_16x16x32_bf16 v[100:103], v[172:175], v[196:199], v[100:103]
	v_mfma_f32_16x16x32_bf16 v[96:99], v[180:183], v[196:199], v[96:99]
	v_mfma_f32_16x16x32_bf16 v[84:87], v[172:175], v[210:213], v[84:87]
	v_mfma_f32_16x16x32_bf16 v[80:83], v[180:183], v[210:213], v[80:83]
	v_mfma_f32_16x16x32_bf16 v[68:71], v[172:175], v[218:221], v[68:71]
	v_mfma_f32_16x16x32_bf16 v[64:67], v[180:183], v[218:221], v[64:67]
	s_barrier
	s_setprio 0
	s_add_i32 s18, s20, s7
	v_lshl_add_u64 v[140:141], v[140:141], 0, s[76:77]
	s_mov_b32 m0, s18
	ds_read_b128 v[184:187], v144 offset:49152
	ds_read_b128 v[188:191], v144 offset:50176
	ds_read_b128 v[192:195], v144 offset:51200
	ds_read_b128 v[196:199], v144 offset:52224
	ds_read_b128 v[206:209], v144 offset:53248
	ds_read_b128 v[210:213], v144 offset:54272
	ds_read_b128 v[214:217], v144 offset:55296
	ds_read_b128 v[218:221], v144 offset:56320
	global_load_lds_dwordx4 v[140:141], off
	s_add_i32 m0, s18, 0x2000
	s_add_u32 s18, s50, 0x40080
	v_lshl_add_u64 v[140:141], v[158:159], 0, s[76:77]
	s_addc_u32 s19, s51, 0
	s_add_i32 s20, s21, s7
	global_load_lds_dwordx4 v[140:141], off
	v_lshl_add_u64 v[140:141], s[18:19], 0, v[132:133]
	s_mov_b32 m0, s20
	s_nop 0
	global_load_lds_dwordx4 v[140:141], off
	v_lshl_add_u64 v[140:141], s[18:19], 0, v[128:129]
	s_add_i32 m0, s20, 0x2000
	s_nop 0
	global_load_lds_dwordx4 v[140:141], off
	v_lshl_add_u64 v[140:141], v[200:201], 0, s[76:77]
	s_mov_b32 m0, s12
	s_nop 0
	global_load_lds_dwordx4 v[140:141], off
	v_lshl_add_u64 v[140:141], v[222:223], 0, s[76:77]
	s_mov_b32 m0, s13
	s_nop 0
	global_load_lds_dwordx4 v[140:141], off
	s_waitcnt vmcnt(8)
	s_waitcnt lgkmcnt(0)
	s_setprio 1
	s_barrier
	v_mfma_f32_16x16x32_bf16 v[60:63], v[146:149], v[184:187], v[60:63]
	v_mfma_f32_16x16x32_bf16 v[56:59], v[154:157], v[184:187], v[56:59]
	v_mfma_f32_16x16x32_bf16 v[44:47], v[146:149], v[192:195], v[44:47]
	v_mfma_f32_16x16x32_bf16 v[40:43], v[154:157], v[192:195], v[40:43]
	v_mfma_f32_16x16x32_bf16 v[28:31], v[146:149], v[206:209], v[28:31]
	v_mfma_f32_16x16x32_bf16 v[24:27], v[154:157], v[206:209], v[24:27]
	v_mfma_f32_16x16x32_bf16 v[12:15], v[146:149], v[214:217], v[12:15]
	v_mfma_f32_16x16x32_bf16 v[8:11], v[154:157], v[214:217], v[8:11]
	v_mfma_f32_16x16x32_bf16 v[60:63], v[150:153], v[188:191], v[60:63]
	v_mfma_f32_16x16x32_bf16 v[56:59], v[164:167], v[188:191], v[56:59]
	v_mfma_f32_16x16x32_bf16 v[44:47], v[150:153], v[196:199], v[44:47]
	v_mfma_f32_16x16x32_bf16 v[40:43], v[164:167], v[196:199], v[40:43]
	v_mfma_f32_16x16x32_bf16 v[28:31], v[150:153], v[210:213], v[28:31]
	v_mfma_f32_16x16x32_bf16 v[24:27], v[164:167], v[210:213], v[24:27]
	v_mfma_f32_16x16x32_bf16 v[12:15], v[150:153], v[218:221], v[12:15]
	v_mfma_f32_16x16x32_bf16 v[8:11], v[164:167], v[218:221], v[8:11]
	s_setprio 0
	s_setprio 1
	v_mfma_f32_16x16x32_bf16 v[52:55], v[168:171], v[184:187], v[52:55]
	v_mfma_f32_16x16x32_bf16 v[48:51], v[176:179], v[184:187], v[48:51]
	v_mfma_f32_16x16x32_bf16 v[36:39], v[168:171], v[192:195], v[36:39]
	v_mfma_f32_16x16x32_bf16 v[32:35], v[176:179], v[192:195], v[32:35]
	v_mfma_f32_16x16x32_bf16 v[20:23], v[168:171], v[206:209], v[20:23]
	v_mfma_f32_16x16x32_bf16 v[16:19], v[176:179], v[206:209], v[16:19]
	v_mfma_f32_16x16x32_bf16 v[4:7], v[168:171], v[214:217], v[4:7]
	v_mfma_f32_16x16x32_bf16 v[0:3], v[176:179], v[214:217], v[0:3]
	v_mfma_f32_16x16x32_bf16 v[52:55], v[172:175], v[188:191], v[52:55]
	v_mfma_f32_16x16x32_bf16 v[48:51], v[180:183], v[188:191], v[48:51]
	v_mfma_f32_16x16x32_bf16 v[36:39], v[172:175], v[196:199], v[36:39]
	v_mfma_f32_16x16x32_bf16 v[32:35], v[180:183], v[196:199], v[32:35]
	v_mfma_f32_16x16x32_bf16 v[20:23], v[172:175], v[210:213], v[20:23]
	v_mfma_f32_16x16x32_bf16 v[16:19], v[180:183], v[210:213], v[16:19]
	v_mfma_f32_16x16x32_bf16 v[4:7], v[172:175], v[218:221], v[4:7]
	v_mfma_f32_16x16x32_bf16 v[0:3], v[180:183], v[218:221], v[0:3]
	s_barrier
	s_setprio 0
	s_add_i32 s63, s63, 2
	s_add_u32 s58, s58, 0x100
	s_addc_u32 s59, s59, 0
	s_add_u32 s47, s47, 0x100
	s_addc_u32 s62, s62, 0
	s_cmp_gt_u32 s63, 13
	s_cbranch_scc0 .LBB0_1138
	s_branch .Lpeel_x_1138
